# attention loop: V tile DMA deferred to the top of the next half-step, which removes the mid-step barrier (one s_barrier per KV tile instead of two); closing wait is vmcnt(0)
# speedup vs baseline: 1.0645x; 1.0157x over previous
.LBB0_389:
	ds_read_b128 v[98:101], v214 offset:49152
	ds_read_b128 v[102:105], v214 offset:49280
	ds_read_b128 v[106:109], v214 offset:57344
	ds_read_b128 v[110:113], v214 offset:57472
	ds_read_b128 v[178:181], v215 offset:49152
	ds_read_b128 v[184:187], v215 offset:49280
	ds_read_b128 v[188:191], v215 offset:57344
	ds_read_b128 v[226:229], v215 offset:57472
	s_waitcnt lgkmcnt(7)
	v_mfma_f32_32x32x16_bf16 v[50:65], v[98:101], v[158:161], v[50:65]
	ds_read_b128 v[98:101], v216 offset:49152
	ds_read_b128 v[230:233], v216 offset:49280
	ds_read_b128 v[234:237], v216 offset:57344
	ds_read_b128 v[238:241], v216 offset:57472
	ds_read_b128 v[242:245], v217 offset:49152
	ds_read_b128 v[246:249], v217 offset:49280
	ds_read_b128 v[250:253], v217 offset:57344
	ds_read_b128 v[192:195], v217 offset:57472
	v_exp_f32_e32 v128, v128
	v_exp_f32_e32 v129, v129
	v_exp_f32_e32 v126, v126
	v_exp_f32_e32 v127, v127
	v_exp_f32_e32 v124, v124
	v_exp_f32_e32 v125, v125
	s_waitcnt lgkmcnt(11)
	v_mfma_f32_32x32x16_bf16 v[50:65], v[178:181], v[154:157], v[50:65]
	v_exp_f32_e32 v122, v122
	v_exp_f32_e32 v116, v116
	v_exp_f32_e32 v117, v117
	v_exp_f32_e32 v114, v114
	v_exp_f32_e32 v115, v115
	v_cvt_pk_bf16_f32 v178, v175, v177
	v_cvt_pk_bf16_f32 v179, v173, v176
	s_waitcnt lgkmcnt(7)
	v_mfma_f32_32x32x16_bf16 v[50:65], v[98:101], v[150:153], v[50:65]
	v_exp_f32_e32 v101, v118
	v_exp_f32_e32 v118, v119
	v_add_f32_e32 v119, 0, v175
	v_add_f32_e32 v119, v177, v119
	v_add_f32_e32 v119, v173, v119
	v_add_f32_e32 v119, v176, v119
	v_add_f32_e32 v119, v171, v119
	s_waitcnt lgkmcnt(3)
	v_mfma_f32_32x32x16_bf16 v[50:65], v[242:245], v[146:149], v[50:65]
	v_exp_f32_e32 v98, v123
	v_exp_f32_e32 v99, v120
	v_exp_f32_e32 v100, v121
	v_cvt_pk_bf16_f32 v180, v171, v174
	v_cvt_pk_bf16_f32 v181, v170, v172
	s_nop 0
	v_permlane32_swap_b32_e32 v178, v180
	v_mfma_f32_32x32x16_bf16 v[50:65], v[102:105], v[142:145], v[50:65]
	v_add_f32_e32 v102, v174, v119
	v_add_f32_e32 v102, v170, v102
	v_add_f32_e32 v102, v172, v102
	v_add_f32_e32 v102, v164, v102
	v_add_f32_e32 v102, v167, v102
	v_add_f32_e32 v102, v163, v102
	v_add_f32_e32 v102, v165, v102
	v_mfma_f32_32x32x16_bf16 v[50:65], v[184:187], v[138:141], v[50:65]
	v_add_f32_e32 v102, v162, v102
	v_add_f32_e32 v102, v169, v102
	v_add_f32_e32 v102, v166, v102
	v_add_f32_e32 v102, v168, v102
	v_add_f32_e32 v102, v128, v102
	v_add_f32_e32 v102, v129, v102
	v_add_f32_e32 v102, v126, v102
	v_mfma_f32_32x32x16_bf16 v[50:65], v[230:233], v[134:137], v[50:65]
	v_add_f32_e32 v102, v127, v102
	v_add_f32_e32 v102, v124, v102
	v_add_f32_e32 v102, v125, v102
	v_add_f32_e32 v102, v122, v102
	v_add_f32_e32 v102, v98, v102
	v_add_f32_e32 v102, v99, v102
	v_add_f32_e32 v102, v100, v102
	s_waitcnt lgkmcnt(2)
	v_mfma_f32_32x32x16_bf16 v[50:65], v[246:249], v[130:133], v[50:65]
	v_add_f32_e32 v102, v101, v102
	v_add_f32_e32 v102, v118, v102
	v_add_f32_e32 v102, v116, v102
	v_add_f32_e32 v102, v117, v102
	v_add_f32_e32 v102, v114, v102
	v_add_f32_e32 v223, v115, v102
	v_mov_b32_e32 v224, v223
	s_nop 1
	v_permlane32_swap_b32_e32 v223, v224
	v_cvt_pk_bf16_f32 v184, v164, v167
	v_cvt_pk_bf16_f32 v185, v163, v165
	v_cvt_pk_bf16_f32 v186, v162, v169
	v_cvt_pk_bf16_f32 v187, v166, v168
	v_cvt_pk_bf16_f32 v230, v128, v129
	v_cvt_pk_bf16_f32 v231, v126, v127
	v_cvt_pk_bf16_f32 v232, v124, v125
	v_cvt_pk_bf16_f32 v233, v122, v98
	v_cvt_pk_bf16_f32 v242, v99, v100
	v_cvt_pk_bf16_f32 v243, v101, v118
	v_cvt_pk_bf16_f32 v244, v116, v117
	v_cvt_pk_bf16_f32 v245, v114, v115
	v_permlane32_swap_b32_e32 v179, v181
	v_permlane32_swap_b32_e32 v184, v186
	v_permlane32_swap_b32_e32 v185, v187
	v_permlane32_swap_b32_e32 v230, v232
	v_permlane32_swap_b32_e32 v231, v233
	v_permlane32_swap_b32_e32 v242, v244
	v_permlane32_swap_b32_e32 v243, v245
	v_mfma_f32_32x32x16_bf16 v[82:97], v[106:109], v[158:161], v[82:97]
	s_add_i32 s6, s38, 63
	v_mfma_f32_32x32x16_bf16 v[82:97], v[188:191], v[154:157], v[82:97]
	v_mfma_f32_32x32x16_bf16 v[82:97], v[234:237], v[150:153], v[82:97]
	s_waitcnt lgkmcnt(1)
	v_mfma_f32_32x32x16_bf16 v[82:97], v[250:253], v[146:149], v[82:97]
	v_mfma_f32_32x32x16_bf16 v[82:97], v[110:113], v[142:145], v[82:97]
	v_add_u32_e32 v110, 0x100, v221
	global_load_dwordx4 v[114:117], v110, s[52:53]
	global_load_dwordx4 v[118:121], v110, s[52:53] offset:32
	global_load_dwordx4 v[98:101], v110, s[52:53] offset:128
	global_load_dwordx4 v[102:105], v110, s[52:53] offset:160
	global_load_dwordx4 v[122:125], v110, s[52:53] offset:64
	global_load_dwordx4 v[126:129], v110, s[52:53] offset:96
	global_load_dwordx4 v[106:109], v110, s[52:53] offset:192
	s_nop 0
	global_load_dwordx4 v[110:113], v110, s[52:53] offset:224
	v_mfma_f32_32x32x16_bf16 v[82:97], v[226:229], v[138:141], v[82:97]
	v_mfma_f32_32x32x16_bf16 v[82:97], v[238:241], v[134:137], v[82:97]
	s_waitcnt lgkmcnt(0)
	v_mfma_f32_32x32x16_bf16 v[82:97], v[192:195], v[130:133], v[82:97]
	s_add_i32 m0, s32, 0x8000
	v_xor_b32_e32 v229, 64, v219
	global_load_lds_dwordx4 v219, s[98:99]
	s_add_i32 m0, s32, 0x8400
	v_add_u32_e32 v229, 0x400, v229
	global_load_lds_dwordx4 v229, s[98:99]
	s_sub_u32 s98, s98, 0x4000
	s_subb_u32 s99, s99, 0
	ds_read_b64_tr_b16 v[188:189], v209 offset:0
	ds_read_b64_tr_b16 v[190:191], v209 offset:0x800
	ds_read_b64_tr_b16 v[192:193], v209 offset:0x1000
	ds_read_b64_tr_b16 v[194:195], v209 offset:0x1800
	ds_read_b64_tr_b16 v[234:235], v209 offset:0x2000
	ds_read_b64_tr_b16 v[236:237], v209 offset:0x2800
	ds_read_b64_tr_b16 v[238:239], v209 offset:0x3000
	ds_read_b64_tr_b16 v[240:241], v209 offset:0x3800
	s_nop 0
	s_waitcnt lgkmcnt(6)
	v_mfma_f32_32x32x16_bf16 v[66:81], v[178:181], v[188:191], v[66:81]
	ds_read_b64_tr_b16 v[188:189], v209 offset:0x200
	ds_read_b64_tr_b16 v[190:191], v209 offset:0xa00
	s_waitcnt lgkmcnt(6)
	v_mfma_f32_32x32x16_bf16 v[66:81], v[184:187], v[192:195], v[66:81]
	ds_read_b64_tr_b16 v[192:193], v209 offset:0x1200
	ds_read_b64_tr_b16 v[194:195], v209 offset:0x1a00
	s_waitcnt lgkmcnt(6)
	v_mfma_f32_32x32x16_bf16 v[66:81], v[230:233], v[234:237], v[66:81]
	ds_read_b64_tr_b16 v[234:235], v209 offset:0x2200
	ds_read_b64_tr_b16 v[236:237], v209 offset:0x2a00
	ds_read_b64_tr_b16 v[246:247], v209 offset:0x3200
	ds_read_b64_tr_b16 v[248:249], v209 offset:0x3a00
	s_waitcnt lgkmcnt(8)
	v_mfma_f32_32x32x16_bf16 v[66:81], v[242:245], v[238:241], v[66:81]
	s_waitcnt lgkmcnt(6)
	v_mfma_f32_32x32x16_bf16 v[34:49], v[178:181], v[188:191], v[34:49]
	ds_read_b64_tr_b16 v[188:189], v209 offset:0x400
	ds_read_b64_tr_b16 v[190:191], v209 offset:0xc00
	s_waitcnt lgkmcnt(6)
	v_mfma_f32_32x32x16_bf16 v[34:49], v[184:187], v[192:195], v[34:49]
	ds_read_b64_tr_b16 v[192:193], v209 offset:0x1400
	ds_read_b64_tr_b16 v[194:195], v209 offset:0x1c00
	s_waitcnt lgkmcnt(6)
	v_mfma_f32_32x32x16_bf16 v[34:49], v[230:233], v[234:237], v[34:49]
	ds_read_b64_tr_b16 v[234:235], v209 offset:0x2400
	ds_read_b64_tr_b16 v[236:237], v209 offset:0x2c00
	ds_read_b64_tr_b16 v[238:239], v209 offset:0x3400
	ds_read_b64_tr_b16 v[240:241], v209 offset:0x3c00
	s_waitcnt lgkmcnt(8)
	v_mfma_f32_32x32x16_bf16 v[34:49], v[242:245], v[246:249], v[34:49]
	s_waitcnt lgkmcnt(6)
	v_mfma_f32_32x32x16_bf16 v[18:33], v[178:181], v[188:191], v[18:33]
	ds_read_b64_tr_b16 v[188:189], v209 offset:0x600
	ds_read_b64_tr_b16 v[190:191], v209 offset:0xe00
	s_waitcnt lgkmcnt(6)
	v_mfma_f32_32x32x16_bf16 v[18:33], v[184:187], v[192:195], v[18:33]
	ds_read_b64_tr_b16 v[192:193], v209 offset:0x1600
	ds_read_b64_tr_b16 v[194:195], v209 offset:0x1e00
	s_waitcnt lgkmcnt(6)
	v_mfma_f32_32x32x16_bf16 v[18:33], v[230:233], v[234:237], v[18:33]
	ds_read_b64_tr_b16 v[234:235], v209 offset:0x2600
	ds_read_b64_tr_b16 v[236:237], v209 offset:0x2e00
	ds_read_b64_tr_b16 v[246:247], v209 offset:0x3600
	ds_read_b64_tr_b16 v[248:249], v209 offset:0x3e00
	s_waitcnt lgkmcnt(8)
	v_mfma_f32_32x32x16_bf16 v[18:33], v[242:245], v[238:241], v[18:33]
	s_waitcnt lgkmcnt(6)
	v_mfma_f32_32x32x16_bf16 v[2:17], v[178:181], v[188:191], v[2:17]
	s_cmp_le_i32 s6, s1
	s_cselect_b64 s[6:7], -1, 0
	s_cmp_gt_i32 s38, s8
	s_cselect_b64 s[54:55], -1, 0
	s_and_b64 s[6:7], s[6:7], s[54:55]
	s_and_b64 vcc, exec, s[6:7]
	s_waitcnt lgkmcnt(4)
	v_mfma_f32_32x32x16_bf16 v[2:17], v[184:187], v[192:195], v[2:17]
	s_waitcnt lgkmcnt(2)
	v_mfma_f32_32x32x16_bf16 v[2:17], v[230:233], v[234:237], v[2:17]
	s_waitcnt lgkmcnt(0)
	v_mfma_f32_32x32x16_bf16 v[2:17], v[242:245], v[246:249], v[2:17]
	s_cbranch_vccnz .LBB0_391
	v_subrev_u32_e32 v178, 64, v222
	v_cmp_gt_u32_e32 vcc, s11, v178
	v_add_u32_e32 v178, 0xffffefa0, v222
	s_nop 0
	v_cndmask_b32_e32 v50, v202, v50, vcc
	v_cmp_lt_u32_e32 vcc, s68, v178
	v_add_u32_e32 v178, 0xffffefbf, v222
	s_nop 0
	v_cndmask_b32_e32 v82, v202, v82, vcc
	v_cmp_lt_u32_e32 vcc, s68, v178
	v_add_u32_e32 v178, 0xffffef9f, v222
	s_nop 0
	v_cndmask_b32_e32 v51, v202, v51, vcc
	v_cmp_lt_u32_e32 vcc, s68, v178
	v_add_u32_e32 v178, 0xffffefbe, v222
	s_nop 0
	v_cndmask_b32_e32 v83, v202, v83, vcc
	v_cmp_lt_u32_e32 vcc, s68, v178
	v_add_u32_e32 v178, 0xffffef9e, v222
	s_nop 0
	v_cndmask_b32_e32 v52, v202, v52, vcc
	v_cmp_lt_u32_e32 vcc, s68, v178
	v_add_u32_e32 v178, 0xffffefbd, v222
	s_nop 0
	v_cndmask_b32_e32 v84, v202, v84, vcc
	v_cmp_lt_u32_e32 vcc, s68, v178
	v_add_u32_e32 v178, 0xffffef9d, v222
	s_nop 0
	v_cndmask_b32_e32 v53, v202, v53, vcc
	v_cmp_lt_u32_e32 vcc, s68, v178
	v_add_u32_e32 v178, 0xffffefb8, v222
	s_nop 0
	v_cndmask_b32_e32 v85, v202, v85, vcc
	v_cmp_lt_u32_e32 vcc, s68, v178
	v_add_u32_e32 v178, 0xffffef98, v222
	s_nop 0
	v_cndmask_b32_e32 v54, v202, v54, vcc
	v_cmp_lt_u32_e32 vcc, s68, v178
	v_add_u32_e32 v178, 0xffffefb7, v222
	s_nop 0
	v_cndmask_b32_e32 v86, v202, v86, vcc
	v_cmp_lt_u32_e32 vcc, s68, v178
	v_add_u32_e32 v178, 0xffffef97, v222
	s_nop 0
	v_cndmask_b32_e32 v55, v202, v55, vcc
	v_cmp_lt_u32_e32 vcc, s68, v178
	v_add_u32_e32 v178, 0xffffefb6, v222
	s_nop 0
	v_cndmask_b32_e32 v87, v202, v87, vcc
	v_cmp_lt_u32_e32 vcc, s68, v178
	v_add_u32_e32 v178, 0xffffef96, v222
	s_nop 0
	v_cndmask_b32_e32 v56, v202, v56, vcc
	v_cmp_lt_u32_e32 vcc, s68, v178
	v_add_u32_e32 v178, 0xffffefb5, v222
	s_nop 0
	v_cndmask_b32_e32 v88, v202, v88, vcc
	v_cmp_lt_u32_e32 vcc, s68, v178
	v_add_u32_e32 v178, 0xffffef95, v222
	s_nop 0
	v_cndmask_b32_e32 v57, v202, v57, vcc
	v_cmp_lt_u32_e32 vcc, s68, v178
	v_add_u32_e32 v178, 0xffffefb0, v222
	s_nop 0
	v_cndmask_b32_e32 v89, v202, v89, vcc
	v_cmp_lt_u32_e32 vcc, s68, v178
	v_add_u32_e32 v178, 0xffffef90, v222
	s_nop 0
	v_cndmask_b32_e32 v58, v202, v58, vcc
	v_cmp_lt_u32_e32 vcc, s68, v178
	v_add_u32_e32 v178, 0xffffefaf, v222
	s_nop 0
	v_cndmask_b32_e32 v90, v202, v90, vcc
	v_cmp_lt_u32_e32 vcc, s68, v178
	v_add_u32_e32 v178, 0xffffef8f, v222
	s_nop 0
	v_cndmask_b32_e32 v59, v202, v59, vcc
	v_cmp_lt_u32_e32 vcc, s68, v178
	v_add_u32_e32 v178, 0xffffefae, v222
	s_nop 0
	v_cndmask_b32_e32 v91, v202, v91, vcc
	v_cmp_lt_u32_e32 vcc, s68, v178
	v_add_u32_e32 v178, 0xffffef8e, v222
	s_nop 0
	v_cndmask_b32_e32 v60, v202, v60, vcc
	v_cmp_lt_u32_e32 vcc, s68, v178
	v_add_u32_e32 v178, 0xffffefad, v222
	s_nop 0
	v_cndmask_b32_e32 v92, v202, v92, vcc
	v_cmp_lt_u32_e32 vcc, s68, v178
	v_add_u32_e32 v178, 0xffffef8d, v222
	s_nop 0
	v_cndmask_b32_e32 v61, v202, v61, vcc
	v_cmp_lt_u32_e32 vcc, s68, v178
	v_add_u32_e32 v178, 0xffffefa8, v222
	s_nop 0
	v_cndmask_b32_e32 v93, v202, v93, vcc
	v_cmp_lt_u32_e32 vcc, s68, v178
	v_add_u32_e32 v178, 0xffffef88, v222
	s_nop 0
	v_cndmask_b32_e32 v62, v202, v62, vcc
	v_cmp_lt_u32_e32 vcc, s68, v178
	v_add_u32_e32 v178, 0xffffefa7, v222
	s_nop 0
	v_cndmask_b32_e32 v94, v202, v94, vcc
	v_cmp_lt_u32_e32 vcc, s68, v178
	v_add_u32_e32 v178, 0xffffef87, v222
	s_nop 0
	v_cndmask_b32_e32 v63, v202, v63, vcc
	v_cmp_lt_u32_e32 vcc, s68, v178
	v_add_u32_e32 v178, 0xffffefa6, v222
	s_nop 0
	v_cndmask_b32_e32 v95, v202, v95, vcc
	v_cmp_lt_u32_e32 vcc, s68, v178
	v_add_u32_e32 v178, 0xffffef86, v222
	s_nop 0
	v_cndmask_b32_e32 v64, v202, v64, vcc
	v_cmp_lt_u32_e32 vcc, s68, v178
	v_add_u32_e32 v178, 0xffffefa5, v222
	s_nop 0
	v_cndmask_b32_e32 v96, v202, v96, vcc
	v_cmp_lt_u32_e32 vcc, s68, v178
	v_add_u32_e32 v178, 0xffffef85, v222
	s_nop 0
	v_cndmask_b32_e32 v65, v202, v65, vcc
	v_cmp_lt_u32_e32 vcc, s68, v178
	s_nop 1
	v_cndmask_b32_e32 v97, v202, v97, vcc
.LBB0_391:
	v_max_f32_e32 v178, v51, v51
	v_max_f32_e32 v179, v50, v50
	v_max_f32_e32 v178, v179, v178
	v_max3_f32 v178, v178, v52, v53
	v_max3_f32 v178, v178, v54, v55
	v_max3_f32 v178, v178, v56, v57
	v_max3_f32 v178, v178, v58, v59
	v_max3_f32 v178, v178, v60, v61
	v_max3_f32 v178, v178, v62, v63
	v_max3_f32 v178, v178, v64, v65
	v_max3_f32 v178, v178, v82, v83
	v_max3_f32 v178, v178, v84, v85
	v_max3_f32 v178, v178, v86, v87
	v_max3_f32 v178, v178, v88, v89
	v_max3_f32 v178, v178, v90, v91
	v_max3_f32 v178, v178, v92, v93
	v_max3_f32 v178, v178, v94, v95
	v_max3_f32 v178, v178, v96, v97
	v_mov_b32_e32 v179, v178
	s_nop 1
	v_permlane32_swap_b32_e32 v178, v179
	v_max_f32_e32 v179, v179, v179
	v_max_f32_e32 v178, v178, v178
	v_max_f32_e32 v178, v178, v179
	v_max_f32_e32 v180, v182, v182
	v_sub_f32_e32 v179, v178, v182
	v_max_f32_e32 v178, v180, v178
	v_sub_f32_e32 v180, v182, v178
	v_mul_f32_e32 v180, 0x3e0293ee, v180
	v_mul_f32_e32 v179, 0x3db504f3, v179
	v_exp_f32_e32 v180, v180
	v_cmp_ge_f32_e32 vcc, s69, v179
	s_cmp_eq_u64 vcc, exec
	s_cselect_b64 s[6:7], -1, 0
	v_cndmask_b32_e64 v225, v180, 1.0, s[6:7]
	v_cmp_gt_f32_e32 vcc, 1.0, v225
	s_cbranch_vccz .LBB0_395
	s_and_saveexec_b64 s[54:55], s[4:5]
	ds_write_b32 v208, v225 offset:128
	s_or_b64 exec, exec, s[54:55]
	s_waitcnt lgkmcnt(0)
	ds_read_b128 v[184:187], v207 offset:224
	ds_read_b128 v[188:191], v207 offset:192
	ds_read_b128 v[192:195], v207 offset:160
	ds_read_b128 v[230:233], v207 offset:128
	s_waitcnt lgkmcnt(3)
	v_pk_mul_f32 v[80:81], v[80:81], v[186:187]
	s_waitcnt lgkmcnt(2)
	v_pk_mul_f32 v[76:77], v[76:77], v[190:191]
	s_waitcnt lgkmcnt(1)
	v_pk_mul_f32 v[72:73], v[72:73], v[194:195]
	s_waitcnt lgkmcnt(0)
	v_pk_mul_f32 v[68:69], v[68:69], v[232:233]
	v_pk_mul_f32 v[78:79], v[78:79], v[184:185]
	v_pk_mul_f32 v[74:75], v[74:75], v[188:189]
	v_pk_mul_f32 v[70:71], v[70:71], v[192:193]
	v_pk_mul_f32 v[66:67], v[66:67], v[230:231]
	v_pk_mul_f32 v[48:49], v[48:49], v[186:187]
	v_pk_mul_f32 v[44:45], v[44:45], v[190:191]
	v_pk_mul_f32 v[40:41], v[40:41], v[194:195]
	v_pk_mul_f32 v[36:37], v[36:37], v[232:233]
	v_pk_mul_f32 v[46:47], v[46:47], v[184:185]
	v_pk_mul_f32 v[42:43], v[42:43], v[188:189]
	v_pk_mul_f32 v[38:39], v[38:39], v[192:193]
	v_pk_mul_f32 v[34:35], v[34:35], v[230:231]
	v_pk_mul_f32 v[32:33], v[32:33], v[186:187]
	v_pk_mul_f32 v[28:29], v[28:29], v[190:191]
	v_pk_mul_f32 v[24:25], v[24:25], v[194:195]
	v_pk_mul_f32 v[20:21], v[20:21], v[232:233]
	v_pk_mul_f32 v[30:31], v[30:31], v[184:185]
	v_pk_mul_f32 v[26:27], v[26:27], v[188:189]
	v_pk_mul_f32 v[22:23], v[22:23], v[192:193]
	v_pk_mul_f32 v[18:19], v[18:19], v[230:231]
	v_pk_mul_f32 v[16:17], v[16:17], v[186:187]
	v_pk_mul_f32 v[12:13], v[12:13], v[190:191]
	v_pk_mul_f32 v[8:9], v[8:9], v[194:195]
	v_pk_mul_f32 v[4:5], v[4:5], v[232:233]
	v_pk_mul_f32 v[14:15], v[14:15], v[184:185]
	v_pk_mul_f32 v[10:11], v[10:11], v[188:189]
	v_pk_mul_f32 v[6:7], v[6:7], v[192:193]
	v_pk_mul_f32 v[2:3], v[2:3], v[230:231]
.LBB0_395:
	v_cndmask_b32_e64 v226, v178, v182, s[6:7]
	v_mul_f32_e32 v178, 0xbe0293ee, v226
	v_fmamk_f32 v50, v50, 0x3e0293ee, v178
	v_fmamk_f32 v51, v51, 0x3e0293ee, v178
	v_fmamk_f32 v52, v52, 0x3e0293ee, v178
	v_fmamk_f32 v53, v53, 0x3e0293ee, v178
	v_fmamk_f32 v54, v54, 0x3e0293ee, v178
	v_fmamk_f32 v55, v55, 0x3e0293ee, v178
	v_fmamk_f32 v56, v56, 0x3e0293ee, v178
	v_fmamk_f32 v57, v57, 0x3e0293ee, v178
	v_fmamk_f32 v58, v58, 0x3e0293ee, v178
	v_fmamk_f32 v59, v59, 0x3e0293ee, v178
	v_fmamk_f32 v60, v60, 0x3e0293ee, v178
	v_fmamk_f32 v61, v61, 0x3e0293ee, v178
	v_fmamk_f32 v62, v62, 0x3e0293ee, v178
	v_fmamk_f32 v63, v63, 0x3e0293ee, v178
	v_fmamk_f32 v64, v64, 0x3e0293ee, v178
	v_fmamk_f32 v65, v65, 0x3e0293ee, v178
	v_exp_f32_e32 v50, v50
	v_exp_f32_e32 v51, v51
	v_exp_f32_e32 v52, v52
	v_exp_f32_e32 v53, v53
	v_exp_f32_e32 v54, v54
	v_exp_f32_e32 v55, v55
	v_exp_f32_e32 v56, v56
	v_exp_f32_e32 v57, v57
	v_exp_f32_e32 v58, v58
	v_exp_f32_e32 v59, v59
	v_exp_f32_e32 v60, v60
	v_exp_f32_e32 v61, v61
	v_exp_f32_e32 v62, v62
	v_exp_f32_e32 v63, v63
	v_exp_f32_e32 v64, v64
	v_exp_f32_e32 v65, v65
	v_fmamk_f32 v82, v82, 0x3e0293ee, v178
	v_fmamk_f32 v83, v83, 0x3e0293ee, v178
	v_fmamk_f32 v84, v84, 0x3e0293ee, v178
	v_fmamk_f32 v85, v85, 0x3e0293ee, v178
	v_fmamk_f32 v86, v86, 0x3e0293ee, v178
	v_fmamk_f32 v87, v87, 0x3e0293ee, v178
	v_fmamk_f32 v88, v88, 0x3e0293ee, v178
	v_fmamk_f32 v89, v89, 0x3e0293ee, v178
	v_fmamk_f32 v90, v90, 0x3e0293ee, v178
	v_fmamk_f32 v91, v91, 0x3e0293ee, v178
	v_fmamk_f32 v92, v92, 0x3e0293ee, v178
	v_fmamk_f32 v93, v93, 0x3e0293ee, v178
	v_fmamk_f32 v94, v94, 0x3e0293ee, v178
	v_fmamk_f32 v95, v95, 0x3e0293ee, v178
	v_fmamk_f32 v96, v96, 0x3e0293ee, v178
	v_fmac_f32_e32 v178, 0x3e0293ee, v97
	s_waitcnt lgkmcnt(0)
	s_waitcnt vmcnt(0)
	s_barrier
	s_add_i32 m0, s32, 0x0
	v_add_u32_e32 v229, 0x80, v218
	global_load_lds_dwordx4 v218, s[100:101]
	s_add_i32 m0, s32, 0x400
	s_nop 0
	global_load_lds_dwordx4 v229, s[100:101]
	s_sub_u32 s100, s100, 0x4000
	s_subb_u32 s101, s101, 0
	ds_read_b128 v[230:233], v214 offset:32768
	ds_read_b128 v[234:237], v214 offset:40960
	ds_read_b128 v[238:241], v215 offset:32768
	ds_read_b128 v[242:245], v215 offset:40960
	ds_read_b128 v[180:183], v216 offset:32768
	ds_read_b128 v[184:187], v216 offset:40960
	ds_read_b128 v[246:249], v217 offset:32768
	ds_read_b128 v[250:253], v217 offset:40960
	v_exp_f32_e32 v97, v178
	v_add_f32_e32 v178, 0, v50
	v_add_f32_e32 v178, v51, v178
	s_waitcnt lgkmcnt(7)
	v_mfma_f32_32x32x16_bf16 v[114:129], v[230:233], v[158:161], v[114:129]
	v_add_f32_e32 v178, v52, v178
	v_add_f32_e32 v178, v53, v178
	v_add_f32_e32 v178, v54, v178
	v_add_f32_e32 v178, v55, v178
	v_add_f32_e32 v178, v56, v178
	v_add_f32_e32 v178, v57, v178
	v_add_f32_e32 v178, v58, v178
	s_waitcnt lgkmcnt(6)
	v_mfma_f32_32x32x16_bf16 v[98:113], v[234:237], v[158:161], v[98:113]
	ds_read_b128 v[230:233], v214 offset:32896
	ds_read_b128 v[234:237], v214 offset:41088
	v_add_f32_e32 v178, v59, v178
	v_add_f32_e32 v178, v60, v178
	v_add_f32_e32 v178, v61, v178
	v_exp_f32_e32 v82, v82
	v_add_f32_e32 v178, v62, v178
	v_exp_f32_e32 v83, v83
	s_waitcnt lgkmcnt(7)
	v_mfma_f32_32x32x16_bf16 v[114:129], v[238:241], v[154:157], v[114:129]
	v_add_f32_e32 v178, v63, v178
	v_exp_f32_e32 v84, v84
	v_add_f32_e32 v178, v64, v178
	v_exp_f32_e32 v85, v85
	v_add_f32_e32 v178, v65, v178
	v_exp_f32_e32 v86, v86
	v_add_f32_e32 v178, v82, v178
	s_waitcnt lgkmcnt(6)
	v_mfma_f32_32x32x16_bf16 v[98:113], v[242:245], v[154:157], v[98:113]
	ds_read_b128 v[238:241], v215 offset:32896
	ds_read_b128 v[242:245], v215 offset:41088
	v_exp_f32_e32 v87, v87
	v_add_f32_e32 v178, v83, v178
	v_exp_f32_e32 v88, v88
	v_add_f32_e32 v178, v84, v178
	v_exp_f32_e32 v89, v89
	v_add_f32_e32 v178, v85, v178
	s_waitcnt lgkmcnt(7)
	v_mfma_f32_32x32x16_bf16 v[114:129], v[180:183], v[150:153], v[114:129]
	v_exp_f32_e32 v90, v90
	v_add_f32_e32 v178, v86, v178
	v_exp_f32_e32 v91, v91
	v_add_f32_e32 v178, v87, v178
	v_exp_f32_e32 v92, v92
	v_add_f32_e32 v178, v88, v178
	v_exp_f32_e32 v93, v93
	s_waitcnt lgkmcnt(6)
	v_mfma_f32_32x32x16_bf16 v[98:113], v[184:187], v[150:153], v[98:113]
	ds_read_b128 v[180:183], v216 offset:32896
	ds_read_b128 v[184:187], v216 offset:41088
	v_add_f32_e32 v178, v89, v178
	v_exp_f32_e32 v94, v94
	v_add_f32_e32 v178, v90, v178
	v_exp_f32_e32 v95, v95
	v_add_f32_e32 v178, v91, v178
	v_exp_f32_e32 v96, v96
	s_waitcnt lgkmcnt(7)
	v_mfma_f32_32x32x16_bf16 v[114:129], v[246:249], v[146:149], v[114:129]
	v_add_f32_e32 v178, v92, v178
	v_add_f32_e32 v178, v93, v178
	v_add_f32_e32 v178, v94, v178
	v_add_f32_e32 v178, v95, v178
	v_add_f32_e32 v178, v96, v178
	v_add_f32_e32 v227, v97, v178
	v_mov_b32_e32 v228, v227
	s_waitcnt lgkmcnt(6)
	v_mfma_f32_32x32x16_bf16 v[98:113], v[250:253], v[146:149], v[98:113]
	ds_read_b128 v[246:249], v217 offset:32896
	ds_read_b128 v[250:253], v217 offset:41088
	v_permlane32_swap_b32_e32 v227, v228
	s_waitcnt lgkmcnt(7)
	v_mfma_f32_32x32x16_bf16 v[114:129], v[230:233], v[142:145], v[114:129]
	s_waitcnt lgkmcnt(6)
	v_mfma_f32_32x32x16_bf16 v[98:113], v[234:237], v[142:145], v[98:113]
	s_waitcnt lgkmcnt(5)
	v_mfma_f32_32x32x16_bf16 v[114:129], v[238:241], v[138:141], v[114:129]
	s_waitcnt lgkmcnt(4)
	v_mfma_f32_32x32x16_bf16 v[98:113], v[242:245], v[138:141], v[98:113]
	s_waitcnt lgkmcnt(3)
	v_mfma_f32_32x32x16_bf16 v[114:129], v[180:183], v[134:137], v[114:129]
	s_waitcnt lgkmcnt(2)
	v_mfma_f32_32x32x16_bf16 v[98:113], v[184:187], v[134:137], v[98:113]
	v_cvt_pk_bf16_f32 v178, v50, v51
	v_cvt_pk_bf16_f32 v179, v52, v53
	s_waitcnt lgkmcnt(1)
	v_mfma_f32_32x32x16_bf16 v[114:129], v[246:249], v[130:133], v[114:129]
	v_cvt_pk_bf16_f32 v180, v54, v55
	v_cvt_pk_bf16_f32 v181, v56, v57
	v_cvt_pk_bf16_f32 v182, v58, v59
	v_cvt_pk_bf16_f32 v183, v60, v61
	s_nop 0
	v_permlane32_swap_b32_e32 v178, v180
	s_waitcnt lgkmcnt(0)
	v_mfma_f32_32x32x16_bf16 v[98:113], v[250:253], v[130:133], v[98:113]
	v_cvt_pk_bf16_f32 v184, v62, v63
	v_cvt_pk_bf16_f32 v185, v64, v65
	v_cvt_pk_bf16_f32 v186, v82, v83
	v_cvt_pk_bf16_f32 v187, v84, v85
	v_cvt_pk_bf16_f32 v188, v86, v87
	v_cvt_pk_bf16_f32 v189, v88, v89
	v_cvt_pk_bf16_f32 v190, v90, v91
	v_cvt_pk_bf16_f32 v191, v92, v93
	v_cvt_pk_bf16_f32 v192, v94, v95
	v_cvt_pk_bf16_f32 v193, v96, v97
	v_permlane32_swap_b32_e32 v179, v181
	v_permlane32_swap_b32_e32 v182, v184
	v_permlane32_swap_b32_e32 v183, v185
	v_permlane32_swap_b32_e32 v186, v188
	v_permlane32_swap_b32_e32 v187, v189
	v_permlane32_swap_b32_e32 v190, v192
	v_permlane32_swap_b32_e32 v191, v193
	s_add_i32 s6, s33, 1
	s_cmp_lt_i32 s6, s27
	s_cselect_b64 s[54:55], -1, 0
	s_cmp_ge_i32 s6, s27
	s_cbranch_scc1 .LBB0_397
	global_load_dwordx4 v[50:53], v221, s[52:53]
	global_load_dwordx4 v[54:57], v221, s[52:53] offset:32
	global_load_dwordx4 v[82:85], v221, s[52:53] offset:128
	global_load_dwordx4 v[86:89], v221, s[52:53] offset:160
	global_load_dwordx4 v[58:61], v221, s[52:53] offset:64
	global_load_dwordx4 v[62:65], v221, s[52:53] offset:96
	global_load_dwordx4 v[90:93], v221, s[52:53] offset:192
	global_load_dwordx4 v[94:97], v221, s[52:53] offset:224
	s_add_i32 m0, s32, 0xc000
	v_xor_b32_e32 v229, 64, v219
	global_load_lds_dwordx4 v219, s[98:99]
	s_add_i32 m0, s32, 0xc400
	v_add_u32_e32 v229, 0x400, v229
	global_load_lds_dwordx4 v229, s[98:99]
	s_sub_u32 s98, s98, 0x4000
	s_subb_u32 s99, s99, 0

.LBB0_399:
	v_max_f32_e32 v178, v115, v115
	v_max_f32_e32 v179, v114, v114
	v_max_f32_e32 v178, v179, v178
	v_max3_f32 v178, v178, v116, v117
	v_max3_f32 v178, v178, v118, v119
	v_max3_f32 v178, v178, v120, v121
	v_max3_f32 v178, v178, v122, v123
	v_max3_f32 v178, v178, v124, v125
	v_max3_f32 v178, v178, v126, v127
	v_max3_f32 v178, v178, v128, v129
	v_max3_f32 v178, v178, v98, v99
	v_max3_f32 v178, v178, v100, v101
	v_max3_f32 v178, v178, v102, v103
	v_max3_f32 v178, v178, v104, v105
	v_max3_f32 v178, v178, v106, v107
	v_max3_f32 v178, v178, v108, v109
	v_max3_f32 v178, v178, v110, v111
	v_max3_f32 v178, v178, v112, v113
	v_mov_b32_e32 v179, v178
	s_nop 1
	v_permlane32_swap_b32_e32 v178, v179
	v_max_f32_e32 v179, v179, v179
	v_max_f32_e32 v178, v178, v178
	v_max_f32_e32 v178, v178, v179
	v_sub_f32_e32 v179, v178, v226
	v_mul_f32_e32 v179, 0x3db504f3, v179
	v_cmp_ge_f32_e32 vcc, s69, v179
	s_cmp_eq_u64 vcc, exec
	s_cselect_b64 s[6:7], -1, 0
	s_andn2_b64 vcc, exec, s[54:55]
.LBB0_401:
	v_max_f32_e32 v162, v226, v226
	v_max_f32_e32 v162, v162, v178
	v_sub_f32_e32 v163, v226, v162
	v_mul_f32_e32 v163, 0x3e0293ee, v163
	v_exp_f32_e32 v163, v163
	s_nop 0
	v_cndmask_b32_e64 v178, v163, 1.0, s[6:7]
	v_cmp_gt_f32_e32 vcc, 1.0, v178
	s_cbranch_vccz .LBB0_405
	s_and_saveexec_b64 s[54:55], s[4:5]
	ds_write_b32 v208, v178 offset:128
	s_or_b64 exec, exec, s[54:55]
	s_waitcnt lgkmcnt(0)
	ds_read_b128 v[164:167], v207 offset:224
	ds_read_b128 v[168:171], v207 offset:192
	ds_read_b128 v[172:175], v207 offset:160
	ds_read_b128 v[180:183], v207 offset:128
	s_waitcnt lgkmcnt(3)
	v_pk_mul_f32 v[80:81], v[80:81], v[166:167]
	s_waitcnt lgkmcnt(2)
	v_pk_mul_f32 v[76:77], v[76:77], v[170:171]
	s_waitcnt lgkmcnt(1)
	v_pk_mul_f32 v[72:73], v[72:73], v[174:175]
	s_waitcnt lgkmcnt(0)
	v_pk_mul_f32 v[68:69], v[68:69], v[182:183]
	v_pk_mul_f32 v[78:79], v[78:79], v[164:165]
	v_pk_mul_f32 v[74:75], v[74:75], v[168:169]
	v_pk_mul_f32 v[70:71], v[70:71], v[172:173]
	v_pk_mul_f32 v[66:67], v[66:67], v[180:181]
	v_pk_mul_f32 v[48:49], v[48:49], v[166:167]
	v_pk_mul_f32 v[44:45], v[44:45], v[170:171]
	v_pk_mul_f32 v[40:41], v[40:41], v[174:175]
	v_pk_mul_f32 v[36:37], v[36:37], v[182:183]
	v_pk_mul_f32 v[46:47], v[46:47], v[164:165]
	v_pk_mul_f32 v[42:43], v[42:43], v[168:169]
	v_pk_mul_f32 v[38:39], v[38:39], v[172:173]
	v_pk_mul_f32 v[34:35], v[34:35], v[180:181]
	v_pk_mul_f32 v[32:33], v[32:33], v[166:167]
	v_pk_mul_f32 v[28:29], v[28:29], v[170:171]
	v_pk_mul_f32 v[24:25], v[24:25], v[174:175]
	v_pk_mul_f32 v[20:21], v[20:21], v[182:183]
	v_pk_mul_f32 v[30:31], v[30:31], v[164:165]
	v_pk_mul_f32 v[26:27], v[26:27], v[168:169]
	v_pk_mul_f32 v[22:23], v[22:23], v[172:173]
	v_pk_mul_f32 v[18:19], v[18:19], v[180:181]
	v_pk_mul_f32 v[16:17], v[16:17], v[166:167]
	v_pk_mul_f32 v[12:13], v[12:13], v[170:171]
	v_pk_mul_f32 v[8:9], v[8:9], v[174:175]
	v_pk_mul_f32 v[4:5], v[4:5], v[182:183]
	v_pk_mul_f32 v[14:15], v[14:15], v[164:165]
	v_pk_mul_f32 v[10:11], v[10:11], v[168:169]
	v_pk_mul_f32 v[6:7], v[6:7], v[172:173]
	v_pk_mul_f32 v[2:3], v[2:3], v[180:181]
.LBB0_405:
	v_cndmask_b32_e64 v182, v162, v226, s[6:7]
	v_mul_f32_e32 v180, 0xbe0293ee, v182
	v_mov_b32_e32 v183, v180
	v_fmamk_f32 v162, v114, 0x3e0293ee, v180
	v_fmamk_f32 v163, v115, 0x3e0293ee, v180
	v_fmamk_f32 v164, v116, 0x3e0293ee, v180
	v_fmamk_f32 v165, v117, 0x3e0293ee, v180
	v_fmamk_f32 v166, v118, 0x3e0293ee, v180
	v_fmamk_f32 v167, v119, 0x3e0293ee, v180
	v_fmamk_f32 v168, v120, 0x3e0293ee, v180
	v_fmamk_f32 v169, v121, 0x3e0293ee, v180
	v_fmamk_f32 v179, v122, 0x3e0293ee, v180
	v_fmamk_f32 v181, v123, 0x3e0293ee, v180
	v_fmamk_f32 v124, v124, 0x3e0293ee, v180
	v_fmamk_f32 v125, v125, 0x3e0293ee, v180
	v_fmamk_f32 v126, v126, 0x3e0293ee, v180
	v_fmamk_f32 v127, v127, 0x3e0293ee, v180
	v_fmamk_f32 v128, v128, 0x3e0293ee, v180
	v_fmac_f32_e32 v183, 0x3e0293ee, v129
	v_exp_f32_e32 v175, v162
	v_exp_f32_e32 v177, v163
	v_exp_f32_e32 v173, v164
	v_exp_f32_e32 v176, v165
	v_exp_f32_e32 v171, v166
	v_exp_f32_e32 v174, v167
	v_exp_f32_e32 v170, v168
	v_exp_f32_e32 v172, v169
	v_exp_f32_e32 v164, v179
	v_exp_f32_e32 v167, v181
	v_exp_f32_e32 v163, v124
	v_exp_f32_e32 v165, v125
	v_exp_f32_e32 v162, v126
	v_exp_f32_e32 v169, v127
	v_exp_f32_e32 v166, v128
	v_exp_f32_e32 v168, v183
	v_pk_fma_f32 v[128:129], v[98:99], s[16:17], v[180:181] op_sel_hi:[1,0,0]
	v_add_f32_e32 v98, v223, v224
	v_fmac_f32_e32 v98, v220, v213
	v_add_f32_e32 v213, v227, v228
	s_addk_i32 s38, 0xff80
	s_add_i32 s33, s33, 2
	v_pk_fma_f32 v[114:115], v[112:113], s[16:17], v[180:181] op_sel_hi:[1,0,0]
	v_pk_fma_f32 v[116:117], v[110:111], s[16:17], v[180:181] op_sel_hi:[1,0,0]
	v_pk_fma_f32 v[118:119], v[108:109], s[16:17], v[180:181] op_sel_hi:[1,0,0]
	v_pk_fma_f32 v[120:121], v[106:107], s[16:17], v[180:181] op_sel_hi:[1,0,0]
	v_pk_fma_f32 v[122:123], v[104:105], s[16:17], v[180:181] op_sel_hi:[1,0,0]
	v_pk_fma_f32 v[124:125], v[102:103], s[16:17], v[180:181] op_sel_hi:[1,0,0]
	v_pk_fma_f32 v[126:127], v[100:101], s[16:17], v[180:181] op_sel_hi:[1,0,0]
	v_fmac_f32_e32 v213, v98, v225
	v_add_u32_e32 v221, 0xfffffe00, v221
	s_cmp_ge_i32 s33, s27
	v_add_u32_e32 v222, 0x80, v222
	s_waitcnt lgkmcnt(0)
	s_waitcnt vmcnt(0)
	s_barrier
	s_cbranch_scc1 .LBB0_408
	v_mov_b32_e32 v220, v178
	s_add_i32 m0, s32, 0x4000
	v_add_u32_e32 v229, 0x80, v218
	global_load_lds_dwordx4 v218, s[100:101]
	s_add_i32 m0, s32, 0x4400
	s_nop 0
	global_load_lds_dwordx4 v229, s[100:101]
	s_sub_u32 s100, s100, 0x4000
	s_subb_u32 s101, s101, 0
	s_branch .LBB0_389

.LBB0_408:
	s_cmp_eq_u32 s33, s27
	s_cbranch_scc0 .Lat_x_nov
	s_add_i32 m0, s32, 0x4000
	v_add_u32_e32 v229, 0x80, v218
	global_load_lds_dwordx4 v218, s[100:101]
	s_add_i32 m0, s32, 0x4400
	s_nop 0
	global_load_lds_dwordx4 v229, s[100:101]
	s_sub_u32 s100, s100, 0x4000
	s_subb_u32 s101, s101, 0
